# v82 + EpiS1 SLOC stores plain (write-back L2): the consumer is now the same workgroup
# speedup vs baseline: 1.0008x; 1.0008x over previous
.LBB0_256:
	s_add_u32 s20, s78, 0x4e00000
	s_addc_u32 s18, s79, 0
	s_lshl_b32 s0, s62, 8
	s_add_i32 s0, s0, s39
	v_or_b32_e32 v68, s0, v84
	v_lshl_or_b32 v67, s38, 7, v67
	s_and_b32 s21, s18, 0xffff
	s_mov_b32 s23, 0x20000
	s_mov_b32 s22, 0x7ffffff0
	v_lshl_or_b32 v67, v68, 9, v67
	s_waitcnt vmcnt(0)
	s_barrier
	buffer_store_dwordx4 v[62:65], v67, s[20:23], 0 offen
	buffer_store_dwordx4 v[58:61], v67, s[20:23], 0 offen offset:64
	v_cmp_eq_u32_e32 vcc, 0, v66
	s_nop 0
	v_add_u32_e32 v58, 0x2000, v67
	buffer_store_dwordx4 v[54:57], v58, s[20:23], 0 offen
	buffer_store_dwordx4 v[50:53], v58, s[20:23], 0 offen offset:64
	s_nop 1
	v_add_u32_e32 v50, 0x4000, v67
	buffer_store_dwordx4 v[46:49], v50, s[20:23], 0 offen
	buffer_store_dwordx4 v[42:45], v50, s[20:23], 0 offen offset:64
	s_nop 1
	v_add_u32_e32 v42, 0x6000, v67
	buffer_store_dwordx4 v[38:41], v42, s[20:23], 0 offen
	buffer_store_dwordx4 v[34:37], v42, s[20:23], 0 offen offset:64
	s_nop 1
	v_add_u32_e32 v34, 0x10000, v67
	buffer_store_dwordx4 v[30:33], v34, s[20:23], 0 offen
	buffer_store_dwordx4 v[26:29], v34, s[20:23], 0 offen offset:64
	s_nop 1
	v_add_u32_e32 v26, 0x12000, v67
	buffer_store_dwordx4 v[22:25], v26, s[20:23], 0 offen
	buffer_store_dwordx4 v[18:21], v26, s[20:23], 0 offen offset:64
	s_nop 1
	v_add_u32_e32 v18, 0x14000, v67
	buffer_store_dwordx4 v[14:17], v18, s[20:23], 0 offen
	buffer_store_dwordx4 v[10:13], v18, s[20:23], 0 offen offset:64
	s_nop 1
	v_add_u32_e32 v10, 0x16000, v67
	buffer_store_dwordx4 v[6:9], v10, s[20:23], 0 offen
	buffer_store_dwordx4 v[2:5], v10, s[20:23], 0 offen offset:64
	s_waitcnt vmcnt(0)
	s_waitcnt vmcnt(0)
	s_barrier
	v_readlane_b32 s96, v254, 37
	v_mov_b32_e32 v3, 0
	s_bfe_u32 s27, s96, 0x10003
	s_lshl_b32 s27, s27, 8
	s_lshl_b32 s38, s24, 8
	s_add_u32 s38, s78, s38
	s_addc_u32 s39, s79, 0
	s_add_u32 s38, s38, 0xe81c000
	s_addc_u32 s39, s39, 0
	s_add_u32 s40, s78, 0xe804000
	s_addc_u32 s41, s79, 0
	v_and_b32_e32 v152, 63, v66
	v_lshl_or_b32 v152, s24, 6, v152
	v_lshlrev_b32_e32 v152, 3, v152
	v_and_b32_e32 v7, 63, v66
	v_lshl_or_b32 v4, s24, 6, v7
	v_ashrrev_i32_e32 v5, 31, v4
	v_lshl_add_u64 v[4:5], v[4:5], 3, s[78:79]
	v_add_co_u32_e32 v4, vcc, 0xe800000, v4
	s_add_i32 s0, 0, 0x20040
	s_nop 0
	v_addc_co_u32_e32 v5, vcc, 0, v5, vcc
	global_load_dwordx2 v[4:5], v[4:5], off
	v_or_b32_e32 v10, 0xc00, v66
	v_lshrrev_b32_e32 v11, 6, v66
	v_lshlrev_b32_e32 v13, 3, v66
	v_or_b32_e32 v6, 0x400, v66
	v_lshl_add_u32 v33, v7, 3, s0
	v_lshlrev_b32_e32 v7, 2, v7
	v_lshlrev_b32_e32 v39, 4, v10
	v_or_b32_e32 v8, 0x800, v66
	v_or_b32_e32 v12, 0x1000, v66
	v_add_u32_e32 v24, s0, v13
	v_cmp_eq_u32_e64 s[0:1], 1, v11
	v_cmp_eq_u32_e64 s[16:17], 2, v11
	v_cmp_eq_u32_e64 s[4:5], 3, v11
	v_cmp_eq_u32_e64 s[6:7], 4, v11
	v_cmp_eq_u32_e64 s[8:9], 5, v11
	v_cmp_eq_u32_e64 s[10:11], 6, v11
	v_cmp_eq_u32_e64 s[12:13], 7, v11
	v_cmp_eq_u32_e64 s[14:15], 8, v11
	v_lshrrev_b32_e32 v35, 3, v6
	v_lshlrev_b32_e32 v37, 4, v6
	v_lshl_or_b32 v6, v11, 14, v7
	v_mov_b32_e32 v9, 2.0
	v_or_b32_e32 v18, 0x1c00, v66
	v_and_b32_e32 v20, 56, v13
	v_lshl_add_u32 v25, v12, 4, 0
	v_lshlrev_b32_e32 v38, 4, v8
	v_lshlrev_b32_e32 v40, 4, v12
	v_lshlrev_b32_e32 v15, 9, v1
	v_or_b32_e32 v14, 0x1400, v66
	v_lshl_add_u32 v31, v18, 4, 0
	v_lshlrev_b32_e32 v43, 4, v18
	v_lshl_add_u32 v18, v20, 2, 0
	v_lshl_add_u32 v27, v14, 4, 0
	v_lshlrev_b32_e32 v41, 4, v14
	v_add_u32_e32 v45, v18, v15
	v_add_u32_e32 v17, 0x200, v66
	v_or_b32_e32 v16, 0x1800, v66
	v_lshl_add_u32 v29, v16, 4, 0
	v_lshrrev_b32_e32 v34, 3, v17
	v_lshlrev_b32_e32 v42, 4, v16
	v_add_u32_e32 v19, 0x600, v66
	v_lshrrev_b32_e32 v36, 3, v19
	v_lshl_add_u32 v23, v66, 4, 0
	v_lshlrev_b32_e32 v19, 9, v34
	v_lshlrev_b32_e32 v21, 9, v35
	v_lshlrev_b32_e32 v22, 9, v36
	s_lshl_b32 s19, s24, 9
	s_mov_b64 s[58:59], 0
	v_lshlrev_b32_e32 v2, 4, v66
	s_mov_b32 s21, 0xffff
	v_add_u32_e32 v26, 0x12000, v23
	v_add_u32_e32 v28, 0x16000, v23
	v_add_u32_e32 v30, 0x1a000, v23
	v_add_u32_e32 v32, 0x1e000, v23
	v_add_u32_e32 v44, 0, v6
	s_mov_b32 s24, 0xffff0000
	s_movk_i32 s25, 0x500
	s_mov_b64 s[22:23], 0x3a00400
	s_mov_b32 s26, 0x3a00000
	v_add_u32_e32 v46, v18, v19
	v_add_u32_e32 v47, v18, v21
	v_add_u32_e32 v48, v18, v22
	v_mov_b32_e32 v18, v3
	v_mov_b32_e32 v19, v3
	s_waitcnt vmcnt(0)
	v_mul_f32_e32 v10, v4, v4
	v_pk_fma_f32 v[10:11], v[4:5], v[4:5], v[10:11] op_sel_hi:[1,1,0] neg_lo:[1,0,0] neg_hi:[1,0,0]
	v_add_f32_e32 v12, v4, v4
	v_mov_b32_e32 v8, v5
	v_mov_b32_e32 v13, v11
	v_pk_mul_f32 v[12:13], v[12:13], v[8:9]
	v_mov_b32_e32 v14, v11
	v_pk_mov_b32 v[10:11], v[10:11], v[12:13] op_sel:[1,0]
	v_mov_b32_e32 v15, v13
	v_pk_mul_f32 v[10:11], v[10:11], v[14:15]
	v_pk_mul_f32 v[16:17], v[12:13], v[12:13] op_sel_hi:[0,1]
	v_pk_fma_f32 v[12:13], v[12:13], v[12:13], v[10:11] op_sel_hi:[0,1,1] neg_lo:[1,0,0] neg_hi:[1,0,0]
	v_pk_mul_f32 v[14:15], v[10:11], v[16:17]
	v_mov_b32_e32 v8, v12
	v_mov_b32_e32 v10, v15
	v_pk_mul_f32 v[14:15], v[12:13], v[8:9] op_sel_hi:[0,1]
	v_pk_fma_f32 v[12:13], v[12:13], v[8:9], v[10:11] op_sel_hi:[0,1,1] neg_lo:[0,0,1] neg_hi:[0,0,1]
	v_pk_mul_f32 v[10:11], v[14:15], v[10:11]
	v_add_f32_e32 v15, v12, v12
	v_mov_b32_e32 v13, v11
	v_mul_f32_e32 v8, v11, v11
	v_pk_fma_f32 v[12:13], v[12:13], v[12:13], v[8:9] op_sel_hi:[1,1,0] neg_lo:[0,0,1] neg_hi:[0,0,1]
	v_pk_mov_b32 v[6:7], v[4:5], v[4:5] op_sel:[1,0]
	v_mov_b32_e32 v10, v12
	v_mov_b32_e32 v14, v12
	v_pk_mul_f32 v[10:11], v[10:11], v[14:15]
	s_nop 0
	v_pk_mov_b32 v[12:13], v[10:11], v[12:13] op_sel:[1,0]
	v_mov_b32_e32 v8, v11
	v_pk_mul_f32 v[14:15], v[12:13], v[8:9]
	v_pk_fma_f32 v[16:17], v[12:13], v[8:9], v[10:11] neg_lo:[1,0,0] neg_hi:[1,0,0]
	v_pk_mul_f32 v[14:15], v[10:11], v[14:15]
	v_mov_b32_e32 v8, v16
	v_mov_b32_e32 v10, v16
	v_mov_b32_e32 v11, v16
	v_mov_b32_e32 v9, v15
	v_mov_b32_e32 v12, v15
	v_mov_b32_e32 v13, v15
	v_pk_mov_b32 v[14:15], v[14:15], v[16:17] op_sel:[1,0]
	v_lshlrev_b32_e32 v16, 1, v20
